# B g=0 half bodies: P[0] converted after 8 elements, s=0 PV MFMAs issued between the remaining softmax groups
# speedup vs baseline: 1.0016x; 1.0016x over previous
; #define LAS __attribute__((address_space(3)))
; __device__ __forceinline__ unsigned cvtpk(float lo, float hi) { f32x2_t v = {lo, hi}; bf16x2_t b = __builtin_convertvector(v, bf16x2_t); return __builtin_bit_cast(unsigned, b); }
; __device__ __forceinline__ s16x4 vtr(const LAS char* p) { return __builtin_bit_cast(s16x4, __builtin_amdgcn_ds_read_tr16_b64_v4i16((LAS v4i16_t*)p)); }
; template <int NK>
; __device__ __forceinline__ void qk32(f32x16& S, const LAS char* Kp, const bf16x8* Q, int ks0, int r32, int hi) {
;     const LAS char* kb = Kp + r32 * KP + hi * 16 + ks0 * 32;
; #pragma unroll
;     for (int ks = 0; ks < NK; ++ks) { const bf16x8 kf = *(const LAS bf16x8*)(kb + ks * 32); S = __builtin_amdgcn_mfma_f32_32x32x16_bf16(kf, Q[ks0 + ks], S, 0, 0, 0); }
; }
; __device__ __forceinline__ void pv32(f32x16 (&O)[4], const bf16x8 (&P)[2], const LAS char* Vp, int lane) {
;     const int i = lane & 15, q = i >> 2, p = i & 3, dsel = (lane >> 4) & 1, h = lane >> 5;
;     const LAS char* vb = Vp + (4 * h + q) * VP + (16 * dsel + 4 * p) * 2;
; #pragma unroll
;     for (int s = 0; s < 2; ++s)
; #pragma unroll
;         for (int db = 0; db < 4; ++db) {
;             const s16x4 lo = vtr(vb + (16 * s) * VP + db * 64), hi4 = vtr(vb + (16 * s + 8) * VP + db * 64);
;             const bf16x8 a = (bf16x8){lo[0], lo[1], lo[2], lo[3], hi4[0], hi4[1], hi4[2], hi4[3]};
;             O[db] = __builtin_amdgcn_mfma_f32_32x32x16_bf16(a, P[s], O[db], 0, 0, 0);
;         }
; }
; template <int MODE>
; __device__ __forceinline__ void soft32(const f32x16& S, bf16x8 (&P)[2], float& l, float dbase, float nslope) {
;     float p[16];
; #pragma unroll
;     for (int r = 0; r < 16; ++r) {
;         float s = S[r];
;         if (MODE >= 1) { const float a = fabsf(dbase - (float)((r & 3) + 8 * (r >> 2))); s = fmaf(nslope, a, s); float e = __builtin_amdgcn_exp2f(s); if (MODE == 2) e = (a <= 64.f) ? e : 0.f; p[r] = e; }
;         else p[r] = __builtin_amdgcn_exp2f(s);
;         l += p[r];
;     }
; #pragma unroll
;     for (int s = 0; s < 2; ++s) { u32x4 w; w.x = cvtpk(p[8 * s + 0], p[8 * s + 1]); w.y = cvtpk(p[8 * s + 2], p[8 * s + 3]); w.z = cvtpk(p[8 * s + 4], p[8 * s + 5]); w.w = cvtpk(p[8 * s + 6], p[8 * s + 7]); P[s] = __builtin_bit_cast(bf16x8, w); }
; }
.LBB0_354:
	s_bitcmp1_b32 s4, 0
	s_cselect_b32 s4, 0x9400, 0
	s_add_i32 s4, s4, 0
	v_add_u32_e32 v82, s4, v153
	v_add_u32_e32 v83, s4, v154
	s_add_i32 s4, s7, 31
	s_cmp_lt_i32 s4, s66
	s_cselect_b64 s[4:5], -1, 0
	s_cmp_gt_u32 s7, s67
	s_cselect_b64 s[26:27], -1, 0
	s_or_b64 s[4:5], s[4:5], s[26:27]
	s_and_b64 vcc, exec, s[4:5]
	v_add_u32_e32 v158, v82, v146
	v_add_u32_e32 v157, v83, v155
	s_cbranch_vccnz .LBB0_356
	ds_read_b128 v[186:189], v158
	ds_read_b128 v[190:193], v158 offset:32
	ds_read_b128 v[194:197], v158 offset:64
	ds_read_b128 v[198:201], v158 offset:96
	ds_read_b128 v[202:205], v158 offset:128
	ds_read_b128 v[206:209], v158 offset:160
	ds_read_b128 v[210:213], v158 offset:192
	ds_read_b128 v[214:217], v158 offset:224
	v_cvt_f32_u32_e32 v159, s7
	s_waitcnt lgkmcnt(7)
	v_mfma_f32_32x32x16_bf16 v[82:97], v[186:189], v[98:101], v[0:15]
	ds_read_b64_tr_b16 v[218:219], v157 offset:17408
	ds_read_b64_tr_b16 v[220:221], v157 offset:19968
	s_waitcnt lgkmcnt(8)
	v_mfma_f32_32x32x16_bf16 v[82:97], v[190:193], v[102:105], v[82:97]
	ds_read_b64_tr_b16 v[222:223], v157 offset:17472
	ds_read_b64_tr_b16 v[224:225], v157 offset:20032
	s_waitcnt lgkmcnt(9)
	v_mfma_f32_32x32x16_bf16 v[82:97], v[194:197], v[106:109], v[82:97]
	ds_read_b64_tr_b16 v[226:227], v157 offset:17536
	ds_read_b64_tr_b16 v[228:229], v157 offset:20096
	s_waitcnt lgkmcnt(10)
	v_mfma_f32_32x32x16_bf16 v[82:97], v[198:201], v[110:113], v[82:97]
	ds_read_b64_tr_b16 v[230:231], v157 offset:17600
	ds_read_b64_tr_b16 v[232:233], v157 offset:20160
	s_waitcnt lgkmcnt(11)
	v_mfma_f32_32x32x16_bf16 v[82:97], v[202:205], v[122:125], v[82:97]
	ds_read_b64_tr_b16 v[234:235], v157 offset:22528
	ds_read_b64_tr_b16 v[236:237], v157 offset:25088
	s_waitcnt lgkmcnt(12)
	v_mfma_f32_32x32x16_bf16 v[82:97], v[206:209], v[126:129], v[82:97]
	ds_read_b64_tr_b16 v[238:239], v157 offset:22592
	ds_read_b64_tr_b16 v[240:241], v157 offset:25152
	s_waitcnt lgkmcnt(13)
	v_mfma_f32_32x32x16_bf16 v[82:97], v[210:213], v[130:133], v[82:97]
	ds_read_b64_tr_b16 v[242:243], v157 offset:22656
	ds_read_b64_tr_b16 v[244:245], v157 offset:25216
	s_waitcnt lgkmcnt(14)
	v_mfma_f32_32x32x16_bf16 v[82:97], v[214:217], v[134:137], v[82:97]
	ds_read_b64_tr_b16 v[246:247], v157 offset:22720
	ds_read_b64_tr_b16 v[248:249], v157 offset:25280
	v_sub_f32_e32 v160, v152, v159
	v_cmp_le_f32_e64 vcc, |v160|, s33
	s_nop 9
	v_fma_f32 v82, v150, |v160|, v82
	v_exp_f32_e32 v82, v82
	s_nop 0
	v_cndmask_b32_e32 v159, 0, v82, vcc
	v_add_f32_e32 v82, v156, v159
	v_add_f32_e32 v156, -1.0, v160
	v_fma_f32 v83, v150, |v156|, v83
	v_exp_f32_e32 v83, v83
	v_cmp_le_f32_e64 vcc, |v156|, s33
	s_nop 1
	v_cndmask_b32_e32 v161, 0, v83, vcc
	v_add_f32_e32 v156, v161, v82
	v_pk_add_f32 v[82:83], v[160:161], s[50:51] op_sel_hi:[0,1]
	v_fma_f32 v84, v150, |v82|, v84
	v_exp_f32_e32 v84, v84
	v_fma_f32 v85, v150, |v83|, v85
	v_exp_f32_e32 v85, v85
	v_cmp_le_f32_e64 vcc, |v82|, s33
	v_cmp_le_f32_e64 s[4:5], |v83|, s33
	s_nop 0
	v_cndmask_b32_e32 v84, 0, v84, vcc
	v_cndmask_b32_e64 v85, 0, v85, s[4:5]
	v_add_f32_e32 v82, v84, v156
	v_add_f32_e32 v156, v85, v82
	v_pk_add_f32 v[82:83], v[160:161], s[44:45] op_sel_hi:[0,1]
	v_fma_f32 v86, v150, |v82|, v86
	v_exp_f32_e32 v86, v86
	v_fma_f32 v87, v150, |v83|, v87
	v_exp_f32_e32 v87, v87
	v_cmp_le_f32_e64 vcc, |v82|, s33
	v_cmp_le_f32_e64 s[4:5], |v83|, s33
	s_nop 0
	v_cndmask_b32_e32 v163, 0, v86, vcc
	v_cndmask_b32_e64 v162, 0, v87, s[4:5]
	v_add_f32_e32 v82, v163, v156
	v_add_f32_e32 v250, v162, v82
	v_pk_add_f32 v[82:83], v[160:161], s[52:53] op_sel_hi:[0,1]
	v_fma_f32 v87, v150, |v82|, v88
	v_exp_f32_e32 v87, v87
	v_fma_f32 v88, v150, |v83|, v89
	v_exp_f32_e32 v88, v88
	v_cmp_le_f32_e64 vcc, |v82|, s33
	v_cmp_le_f32_e64 s[4:5], |v83|, s33
	s_nop 0
	v_cndmask_b32_e32 v164, 0, v87, vcc
	v_cndmask_b32_e64 v89, 0, v88, s[4:5]
	v_add_f32_e32 v82, v164, v250
	v_add_f32_e32 v250, v89, v82
	v_cvt_pk_bf16_f32 v86, v159, v161
	v_cvt_pk_bf16_f32 v87, v84, v85
	v_cvt_pk_bf16_f32 v88, v163, v162
	v_cvt_pk_bf16_f32 v89, v164, v89
	v_pk_add_f32 v[82:83], v[160:161], s[46:47] op_sel_hi:[0,1]
	v_fma_f32 v251, v150, |v82|, v90
	v_exp_f32_e32 v251, v251
	v_fma_f32 v252, v150, |v83|, v91
	s_waitcnt lgkmcnt(14)
	v_mfma_f32_32x32x16_bf16 v[66:81], v[218:221], v[86:89], v[66:81]
	v_exp_f32_e32 v252, v252
	v_cmp_le_f32_e64 vcc, |v82|, s33
	v_cmp_le_f32_e64 s[4:5], |v83|, s33
	s_nop 0
	v_cndmask_b32_e32 v91, 0, v251, vcc
	v_cndmask_b32_e64 v90, 0, v252, s[4:5]
	v_add_f32_e32 v82, v91, v250
	v_add_f32_e32 v250, v90, v82
	v_pk_add_f32 v[82:83], v[160:161], s[54:55] op_sel_hi:[0,1]
	v_fma_f32 v251, v150, |v82|, v92
	v_exp_f32_e32 v251, v251
	v_fma_f32 v252, v150, |v83|, v93
	s_waitcnt lgkmcnt(12)
	v_mfma_f32_32x32x16_bf16 v[50:65], v[222:225], v[86:89], v[50:65]
	v_exp_f32_e32 v252, v252
	v_cmp_le_f32_e64 vcc, |v82|, s33
	v_cmp_le_f32_e64 s[4:5], |v83|, s33
	s_nop 0
	v_cndmask_b32_e32 v93, 0, v251, vcc
	v_cndmask_b32_e64 v92, 0, v252, s[4:5]
	v_add_f32_e32 v82, v93, v250
	v_add_f32_e32 v250, v92, v82
	v_pk_add_f32 v[82:83], v[160:161], s[56:57] op_sel_hi:[0,1]
	v_fma_f32 v251, v150, |v82|, v94
	v_exp_f32_e32 v251, v251
	v_fma_f32 v252, v150, |v83|, v95
	s_waitcnt lgkmcnt(10)
	v_mfma_f32_32x32x16_bf16 v[34:49], v[226:229], v[86:89], v[34:49]
	v_exp_f32_e32 v252, v252
	v_cmp_le_f32_e64 vcc, |v82|, s33
	v_cmp_le_f32_e64 s[4:5], |v83|, s33
	s_nop 0
	v_cndmask_b32_e32 v95, 0, v251, vcc
	v_cndmask_b32_e64 v94, 0, v252, s[4:5]
	v_add_f32_e32 v82, v95, v250
	v_add_f32_e32 v250, v94, v82
	v_pk_add_f32 v[82:83], v[160:161], s[58:59] op_sel_hi:[0,1]
	v_fma_f32 v251, v150, |v82|, v96
	v_exp_f32_e32 v251, v251
	v_fma_f32 v252, v150, |v83|, v97
	s_waitcnt lgkmcnt(8)
	v_mfma_f32_32x32x16_bf16 v[18:33], v[230:233], v[86:89], v[18:33]
	v_exp_f32_e32 v252, v252
	v_cmp_le_f32_e64 vcc, |v82|, s33
	v_cmp_le_f32_e64 s[4:5], |v83|, s33
	v_cvt_pk_bf16_f32 v83, v93, v92
	v_cndmask_b32_e32 v97, 0, v251, vcc
	v_cndmask_b32_e64 v96, 0, v252, s[4:5]
	v_add_f32_e32 v82, v97, v250
	v_add_f32_e32 v156, v96, v82
	v_cvt_pk_bf16_f32 v82, v91, v90
	v_cvt_pk_bf16_f32 v84, v95, v94
	v_cvt_pk_bf16_f32 v85, v97, v96
	s_nop 1
	s_waitcnt lgkmcnt(6)
	v_mfma_f32_32x32x16_bf16 v[66:81], v[234:237], v[82:85], v[66:81]
	s_waitcnt lgkmcnt(4)
	v_mfma_f32_32x32x16_bf16 v[50:65], v[238:241], v[82:85], v[50:65]
	s_waitcnt lgkmcnt(2)
	v_mfma_f32_32x32x16_bf16 v[34:49], v[242:245], v[82:85], v[34:49]
	s_waitcnt lgkmcnt(0)
	v_mfma_f32_32x32x16_bf16 v[18:33], v[246:249], v[82:85], v[18:33]
; #define LAS __attribute__((address_space(3)))
; __device__ __forceinline__ unsigned cvtpk(float lo, float hi) { f32x2_t v = {lo, hi}; bf16x2_t b = __builtin_convertvector(v, bf16x2_t); return __builtin_bit_cast(unsigned, b); }
; __device__ __forceinline__ s16x4 vtr(const LAS char* p) { return __builtin_bit_cast(s16x4, __builtin_amdgcn_ds_read_tr16_b64_v4i16((LAS v4i16_t*)p)); }
; template <int NK>
; __device__ __forceinline__ void qk32(f32x16& S, const LAS char* Kp, const bf16x8* Q, int ks0, int r32, int hi) {
;     const LAS char* kb = Kp + r32 * KP + hi * 16 + ks0 * 32;
; #pragma unroll
;     for (int ks = 0; ks < NK; ++ks) { const bf16x8 kf = *(const LAS bf16x8*)(kb + ks * 32); S = __builtin_amdgcn_mfma_f32_32x32x16_bf16(kf, Q[ks0 + ks], S, 0, 0, 0); }
; }
; __device__ __forceinline__ void pv32(f32x16 (&O)[4], const bf16x8 (&P)[2], const LAS char* Vp, int lane) {
;     const int i = lane & 15, q = i >> 2, p = i & 3, dsel = (lane >> 4) & 1, h = lane >> 5;
;     const LAS char* vb = Vp + (4 * h + q) * VP + (16 * dsel + 4 * p) * 2;
; #pragma unroll
;     for (int s = 0; s < 2; ++s)
; #pragma unroll
;         for (int db = 0; db < 4; ++db) {
;             const s16x4 lo = vtr(vb + (16 * s) * VP + db * 64), hi4 = vtr(vb + (16 * s + 8) * VP + db * 64);
;             const bf16x8 a = (bf16x8){lo[0], lo[1], lo[2], lo[3], hi4[0], hi4[1], hi4[2], hi4[3]};
;             O[db] = __builtin_amdgcn_mfma_f32_32x32x16_bf16(a, P[s], O[db], 0, 0, 0);
;         }
; }
; template <int MODE>
; __device__ __forceinline__ void soft32(const f32x16& S, bf16x8 (&P)[2], float& l, float dbase, float nslope) {
;     float p[16];
; #pragma unroll
;     for (int r = 0; r < 16; ++r) {
;         float s = S[r];
;         if (MODE >= 1) { const float a = fabsf(dbase - (float)((r & 3) + 8 * (r >> 2))); s = fmaf(nslope, a, s); float e = __builtin_amdgcn_exp2f(s); if (MODE == 2) e = (a <= 64.f) ? e : 0.f; p[r] = e; }
;         else p[r] = __builtin_amdgcn_exp2f(s);
;         l += p[r];
;     }
; #pragma unroll
;     for (int s = 0; s < 2; ++s) { u32x4 w; w.x = cvtpk(p[8 * s + 0], p[8 * s + 1]); w.y = cvtpk(p[8 * s + 2], p[8 * s + 3]); w.z = cvtpk(p[8 * s + 4], p[8 * s + 5]); w.w = cvtpk(p[8 * s + 6], p[8 * s + 7]); P[s] = __builtin_bit_cast(bf16x8, w); }
; }
.LBB0_356:
	s_add_i32 s4, s7, 32
	s_add_i32 s5, s7, 63
	s_cmp_lt_i32 s5, s66
	s_cselect_b64 s[26:27], -1, 0
	s_cmp_gt_u32 s4, s67
	s_cselect_b64 s[78:79], -1, 0
	s_or_b64 s[26:27], s[26:27], s[78:79]
	s_and_b64 vcc, exec, s[26:27]
	s_cbranch_vccnz .LBB0_358
	ds_read_b128 v[186:189], v158 offset:8704
	ds_read_b128 v[190:193], v158 offset:8736
	ds_read_b128 v[194:197], v158 offset:8768
	ds_read_b128 v[198:201], v158 offset:8800
	ds_read_b128 v[202:205], v158 offset:8832
	ds_read_b128 v[206:209], v158 offset:8864
	ds_read_b128 v[210:213], v158 offset:8896
	ds_read_b128 v[214:217], v158 offset:8928
	s_waitcnt lgkmcnt(7)
	v_mfma_f32_32x32x16_bf16 v[82:97], v[186:189], v[98:101], v[0:15]
	ds_read_b64_tr_b16 v[218:219], v157 offset:27648
	ds_read_b64_tr_b16 v[220:221], v157 offset:30208
	s_waitcnt lgkmcnt(8)
	v_mfma_f32_32x32x16_bf16 v[82:97], v[190:193], v[102:105], v[82:97]
	ds_read_b64_tr_b16 v[222:223], v157 offset:27712
	ds_read_b64_tr_b16 v[224:225], v157 offset:30272
	s_waitcnt lgkmcnt(9)
	v_mfma_f32_32x32x16_bf16 v[82:97], v[194:197], v[106:109], v[82:97]
	ds_read_b64_tr_b16 v[226:227], v157 offset:27776
	ds_read_b64_tr_b16 v[228:229], v157 offset:30336
	s_waitcnt lgkmcnt(10)
	v_mfma_f32_32x32x16_bf16 v[82:97], v[198:201], v[110:113], v[82:97]
	ds_read_b64_tr_b16 v[230:231], v157 offset:27840
	ds_read_b64_tr_b16 v[232:233], v157 offset:30400
	s_waitcnt lgkmcnt(11)
	v_mfma_f32_32x32x16_bf16 v[82:97], v[202:205], v[122:125], v[82:97]
	ds_read_b64_tr_b16 v[234:235], v157 offset:32768
	ds_read_b64_tr_b16 v[236:237], v157 offset:35328
	s_waitcnt lgkmcnt(12)
	v_mfma_f32_32x32x16_bf16 v[82:97], v[206:209], v[126:129], v[82:97]
	ds_read_b64_tr_b16 v[238:239], v157 offset:32832
	ds_read_b64_tr_b16 v[240:241], v157 offset:35392
	s_waitcnt lgkmcnt(13)
	v_mfma_f32_32x32x16_bf16 v[82:97], v[210:213], v[130:133], v[82:97]
	ds_read_b64_tr_b16 v[242:243], v157 offset:32896
	ds_read_b64_tr_b16 v[244:245], v157 offset:35456
	s_waitcnt lgkmcnt(14)
	v_mfma_f32_32x32x16_bf16 v[82:97], v[214:217], v[134:137], v[82:97]
	ds_read_b64_tr_b16 v[246:247], v157 offset:32960
	ds_read_b64_tr_b16 v[248:249], v157 offset:35520
	v_cvt_f32_u32_e32 v158, s4
	v_sub_f32_e32 v158, v152, v158
	v_cmp_le_f32_e64 vcc, |v158|, s33
	s_nop 8
	v_fma_f32 v82, v150, |v158|, v82
	v_exp_f32_e32 v82, v82
	s_nop 0
	v_cndmask_b32_e32 v159, 0, v82, vcc
	v_add_f32_e32 v82, v156, v159
	v_add_f32_e32 v156, -1.0, v158
	v_fma_f32 v83, v150, |v156|, v83
	v_exp_f32_e32 v83, v83
	v_cmp_le_f32_e64 vcc, |v156|, s33
	s_nop 1
	v_cndmask_b32_e32 v160, 0, v83, vcc
	v_add_f32_e32 v156, v160, v82
	v_pk_add_f32 v[82:83], v[158:159], s[50:51] op_sel_hi:[0,1]
	v_fma_f32 v84, v150, |v82|, v84
	v_exp_f32_e32 v84, v84
	v_fma_f32 v85, v150, |v83|, v85
	v_exp_f32_e32 v85, v85
	v_cmp_le_f32_e64 vcc, |v82|, s33
	v_cmp_le_f32_e64 s[4:5], |v83|, s33
	s_nop 0
	v_cndmask_b32_e32 v84, 0, v84, vcc
	v_cndmask_b32_e64 v85, 0, v85, s[4:5]
	v_add_f32_e32 v82, v84, v156
	v_add_f32_e32 v156, v85, v82
	v_pk_add_f32 v[82:83], v[158:159], s[44:45] op_sel_hi:[0,1]
	v_fma_f32 v86, v150, |v82|, v86
	v_exp_f32_e32 v86, v86
	v_fma_f32 v87, v150, |v83|, v87
	v_exp_f32_e32 v87, v87
	v_cmp_le_f32_e64 vcc, |v82|, s33
	v_cmp_le_f32_e64 s[4:5], |v83|, s33
	s_nop 0
	v_cndmask_b32_e32 v162, 0, v86, vcc
	v_cndmask_b32_e64 v161, 0, v87, s[4:5]
	v_add_f32_e32 v82, v162, v156
	v_add_f32_e32 v250, v161, v82
	v_pk_add_f32 v[82:83], v[158:159], s[52:53] op_sel_hi:[0,1]
	v_fma_f32 v87, v150, |v82|, v88
	v_exp_f32_e32 v87, v87
	v_fma_f32 v88, v150, |v83|, v89
	v_exp_f32_e32 v88, v88
	v_cmp_le_f32_e64 vcc, |v82|, s33
	v_cmp_le_f32_e64 s[4:5], |v83|, s33
	s_nop 0
	v_cndmask_b32_e32 v163, 0, v87, vcc
	v_cndmask_b32_e64 v89, 0, v88, s[4:5]
	v_add_f32_e32 v82, v163, v250
	v_add_f32_e32 v250, v89, v82
	v_cvt_pk_bf16_f32 v86, v159, v160
	v_cvt_pk_bf16_f32 v87, v84, v85
	v_cvt_pk_bf16_f32 v88, v162, v161
	v_cvt_pk_bf16_f32 v89, v163, v89
	v_pk_add_f32 v[82:83], v[158:159], s[46:47] op_sel_hi:[0,1]
	v_fma_f32 v251, v150, |v82|, v90
	v_exp_f32_e32 v251, v251
	v_fma_f32 v252, v150, |v83|, v91
	s_waitcnt lgkmcnt(14)
	v_mfma_f32_32x32x16_bf16 v[66:81], v[218:221], v[86:89], v[66:81]
	v_exp_f32_e32 v252, v252
	v_cmp_le_f32_e64 vcc, |v82|, s33
	v_cmp_le_f32_e64 s[4:5], |v83|, s33
	s_nop 0
	v_cndmask_b32_e32 v91, 0, v251, vcc
	v_cndmask_b32_e64 v90, 0, v252, s[4:5]
	v_add_f32_e32 v82, v91, v250
	v_add_f32_e32 v250, v90, v82
	v_pk_add_f32 v[82:83], v[158:159], s[54:55] op_sel_hi:[0,1]
	v_fma_f32 v251, v150, |v82|, v92
	v_exp_f32_e32 v251, v251
	v_fma_f32 v252, v150, |v83|, v93
	s_waitcnt lgkmcnt(12)
	v_mfma_f32_32x32x16_bf16 v[50:65], v[222:225], v[86:89], v[50:65]
	v_exp_f32_e32 v252, v252
	v_cmp_le_f32_e64 vcc, |v82|, s33
	v_cmp_le_f32_e64 s[4:5], |v83|, s33
	s_nop 0
	v_cndmask_b32_e32 v93, 0, v251, vcc
	v_cndmask_b32_e64 v92, 0, v252, s[4:5]
	v_add_f32_e32 v82, v93, v250
	v_add_f32_e32 v250, v92, v82
	v_pk_add_f32 v[82:83], v[158:159], s[56:57] op_sel_hi:[0,1]
	v_fma_f32 v251, v150, |v82|, v94
	v_exp_f32_e32 v251, v251
	v_fma_f32 v252, v150, |v83|, v95
	s_waitcnt lgkmcnt(10)
	v_mfma_f32_32x32x16_bf16 v[34:49], v[226:229], v[86:89], v[34:49]
	v_exp_f32_e32 v252, v252
	v_cmp_le_f32_e64 vcc, |v82|, s33
	v_cmp_le_f32_e64 s[4:5], |v83|, s33
	s_nop 0
	v_cndmask_b32_e32 v95, 0, v251, vcc
	v_cndmask_b32_e64 v94, 0, v252, s[4:5]
	v_add_f32_e32 v82, v95, v250
	v_add_f32_e32 v250, v94, v82
	v_pk_add_f32 v[82:83], v[158:159], s[58:59] op_sel_hi:[0,1]
	v_fma_f32 v251, v150, |v82|, v96
	v_exp_f32_e32 v251, v251
	v_fma_f32 v252, v150, |v83|, v97
	s_waitcnt lgkmcnt(8)
	v_mfma_f32_32x32x16_bf16 v[18:33], v[230:233], v[86:89], v[18:33]
	v_exp_f32_e32 v252, v252
	v_cmp_le_f32_e64 vcc, |v82|, s33
	v_cmp_le_f32_e64 s[4:5], |v83|, s33
	v_cvt_pk_bf16_f32 v83, v93, v92
	v_cndmask_b32_e32 v97, 0, v251, vcc
	v_cndmask_b32_e64 v96, 0, v252, s[4:5]
	v_add_f32_e32 v82, v97, v250
	v_add_f32_e32 v156, v96, v82
	v_cvt_pk_bf16_f32 v82, v91, v90
	v_cvt_pk_bf16_f32 v84, v95, v94
	v_cvt_pk_bf16_f32 v85, v97, v96
	s_nop 1
	s_waitcnt lgkmcnt(6)
	v_mfma_f32_32x32x16_bf16 v[66:81], v[234:237], v[82:85], v[66:81]
	s_waitcnt lgkmcnt(4)
	v_mfma_f32_32x32x16_bf16 v[50:65], v[238:241], v[82:85], v[50:65]
	s_waitcnt lgkmcnt(2)
	v_mfma_f32_32x32x16_bf16 v[34:49], v[242:245], v[82:85], v[34:49]
	s_waitcnt lgkmcnt(0)
	v_mfma_f32_32x32x16_bf16 v[18:33], v[246:249], v[82:85], v[18:33]
